# attention: K/V tile loads use SGPR base + 32-bit lane offset (no per-tile 64-bit VALU address math); trimmed redundant max/cmp ops
# speedup vs baseline: 1.0140x; 1.0137x over previous
; DI int v_st(int k, int c) { const int kk = (k & ~0xC) | ((k & 4) << 1) | ((k & 8) >> 1); return ((kk >> 3) * 4 + (c >> 5)) * 512 + ((kk & 7) * 32 + (c & 31)) * 2; }
; DI int v_rd_base(int lane) { return ((lane & 3) << 3) | (((lane >> 2) & 3) << 6) | (((lane >> 4) & 1) << 5) | (((lane >> 5) & 1) << 8); }
; #define SLOADA(k0) do { vsA0 = *reinterpret_cast<const bf16x8*>(&Vh[(size_t)((k0) + sr) * LDQ + sc]); vsA1 = *reinterpret_cast<const bf16x8*>(&Vh[(size_t)((k0) + 32 + sr) * LDQ + sc]); \
;     ksA = *reinterpret_cast<const bf16x8*>(&Kh[(size_t)((k0) + kr) * LDQ + kc]); } while (0)
; #define SLOADB(k0) do { vsB0 = *reinterpret_cast<const bf16x8*>(&Vh[(size_t)((k0) + sr) * LDQ + sc]); vsB1 = *reinterpret_cast<const bf16x8*>(&Vh[(size_t)((k0) + 32 + sr) * LDQ + sc]); \
;     ksB = *reinterpret_cast<const bf16x8*>(&Kh[(size_t)((k0) + kr) * LDQ + kc]); } while (0)
; #define SWRITEA(b) do { *(bf16x8*)(V_lds + (b) * SHM_V + vst0) = vsA0; *(bf16x8*)(V_lds + (b) * SHM_V + vst1) = vsA1; *(bf16x8*)(K_lds + (b) * SHM_K + kst) = ksA; } while (0)
; #define SWRITEB(b) do { *(bf16x8*)(V_lds + (b) * SHM_V + vst0) = vsB0; *(bf16x8*)(V_lds + (b) * SHM_V + vst1) = vsB1; *(bf16x8*)(K_lds + (b) * SHM_K + kst) = ksB; } while (0)
; #define SWAIT() asm volatile("s_waitcnt vmcnt(3)" ::: "memory")
; DI void attn_pass(const bf16_t* __restrict__ Qb, const bf16_t* __restrict__ Kh, const bf16_t* __restrict__ Vh, int seq, char* lds, f32x16 (&o)[4], float& l_out) {
;     ...
;     const bf16_t* Qw = Qb + (size_t)(wid * QBLK + r32) * LDQ + hi * 8;
; #pragma unroll
;     for (int d0 = 0; d0 < 4; ++d0) qr[d0] = *reinterpret_cast<const bf16x8*>(Qw + d0 * 16);
;     const int sr = tid >> 4, sc = (tid & 15) * 8, vst0 = v_st(sr, sc), vst1 = v_st(32 + sr, sc);
;     const int kr = tid >> 3, kc = (tid & 7) * 8, kst = KSWZ(kr, kc * 2);
;     const int vb0 = (int)(uintptr_t)V_lds + v_rd_base(lane);
;     bf16x8 vsA0, vsA1, ksA, vsB0, vsB1, ksB;
;     ...
;     f32x16 pA0, pA1, pB0, pB1; float alA, alB; bf16x8 pa0, pa1, pa2, pa3; const int NT = seq / KVBLK;
;     SLOADA(0); asm volatile("s_waitcnt vmcnt(0)" ::: "memory"); SWRITEA(0); __syncthreads();
;     qkt(pA0, pA1, K_lds, qr, negm, r32, hi); partialSM(pA0, pA1, m_reg, negm, alA);
;     SLOADB(KVBLK); if (2 < NT) SLOADA(2 * KVBLK);
;     SWAIT(); SWRITEB(1); __syncthreads();
.LBB0_1037:
	v_mov_b32_e32 v25, v185
	v_lshl_add_u64 v[38:39], v[22:23], 0, v[24:25]
	s_mov_b32 s16, 0x20000
	v_add_co_u32_e32 v22, vcc, s16, v38
	s_mov_b32 s2, 0x30000
	s_nop 0
	v_addc_co_u32_e32 v23, vcc, 0, v39, vcc
	v_add_co_u32_e32 v30, vcc, s2, v38
	v_mov_b32_e32 v21, v185
	s_nop 0
	v_addc_co_u32_e32 v31, vcc, 0, v39, vcc
	v_lshl_add_u64 v[20:21], v[26:27], 0, v[20:21]
	v_add_co_u32_e32 v26, vcc, s16, v20
	v_exp_f32_e32 v207, v0
	s_nop 0
	v_addc_co_u32_e32 v27, vcc, 0, v21, vcc
	v_add_co_u32_e32 v0, vcc, s3, v20
	s_xor_b64 s[16:17], s[6:7], -1
	v_exp_f32_e32 v209, v1
	v_addc_co_u32_e32 v1, vcc, 0, v21, vcc
	s_mov_b32 s6, 0x50000
	v_exp_f32_e32 v183, v2
	v_add_co_u32_e32 v2, vcc, s6, v38
	v_exp_f32_e32 v208, v3
	s_nop 0
	v_addc_co_u32_e32 v3, vcc, 0, v39, vcc
	global_load_dwordx4 v[22:25], v[22:23], off
	s_nop 0
	global_load_dwordx4 v[30:33], v[30:31], off
	v_exp_f32_e32 v181, v4
	v_add_co_u32_e32 v4, vcc, s3, v38
	global_load_dwordx4 v[34:37], v[26:27], off
	v_exp_f32_e32 v206, v5
	v_addc_co_u32_e32 v5, vcc, 0, v39, vcc
	global_load_dwordx4 v[168:171], v[0:1], off
	global_load_dwordx4 v[164:167], v[2:3], off
	global_load_dwordx4 v[160:163], v[4:5], off
	s_cmp_lg_u32 0, -1
	s_cselect_b32 s25, 0, 0
	s_add_i32 s26, s25, 0x4000
	s_add_u32 s18, s18, s23
	v_and_b32_e32 v0, 7, v28
	s_addc_u32 s19, s19, 0
	v_and_b32_e32 v26, 63, v28
	v_mov_b32_e32 v1, v185
	v_lshlrev_b32_e32 v0, 4, v0
	s_add_u32 s4, s18, s4
	v_lshlrev_b32_e32 v3, 4, v26
	v_lshl_add_u64 v[0:1], v[18:19], 0, v[0:1]
	s_addc_u32 s5, s19, s5
	v_lshlrev_b32_e32 v2, 3, v26
	v_lshlrev_b32_e32 v4, 1, v26
	v_and_b32_e32 v3, 0xc0, v3
	v_mov_b32_e32 v202, v0
	s_add_u32 s100, s4, s14
	s_addc_u32 s101, s5, s15
	s_add_u32 s100, s100, 0x13c60000
	s_addc_u32 s101, s101, 0
	v_and_b32_e32 v0, 15, v28
	v_and_b32_e32 v27, 0x3fffffc0, v28
	v_exp_f32_e32 v180, v6
	v_exp_f32_e32 v182, v7
	v_exp_f32_e32 v173, v8
	v_exp_f32_e32 v175, v9
	v_exp_f32_e32 v172, v10
	v_exp_f32_e32 v174, v11
	v_exp_f32_e32 v177, v12
	v_exp_f32_e32 v179, v13
	v_exp_f32_e32 v176, v14
	v_exp_f32_e32 v178, v15
	v_and_b32_e32 v4, 32, v4
	v_and_b32_e32 v5, 0x100, v2
	v_and_or_b32 v2, v2, 24, v3
	s_add_u32 s4, s8, s23
	v_lshlrev_b32_e32 v0, 4, v0
	v_mov_b32_e32 v1, v185
	v_lshl_add_u32 v211, v27, 2, 0
	s_waitcnt vmcnt(3)
	v_or3_b32 v2, v2, v4, v5
	s_addc_u32 s5, s9, 0
	v_lshl_add_u64 v[0:1], v[16:17], 0, v[0:1]
	v_mov_b32_e32 v14, v185
	v_mov_b32_e32 v15, v185
	v_cmp_gt_u32_e64 s[6:7], 32, v26
	v_lshl_add_u32 v212, v29, 2, v211
	v_add_u32_e32 v220, s25, v2
	v_add_u32_e32 v201, s26, v2
	s_waitcnt vmcnt(5)
	ds_write_b128 v214, v[22:25] offset:16384
	s_waitcnt vmcnt(4)
	ds_write_b128 v215, v[30:33] offset:16384
	s_waitcnt vmcnt(3)
	ds_write_b128 v213, v[34:37] offset:40960
	v_mov_b32_e32 v203, v0
	v_add_u32_e32 v204, 0x10000, v0
	s_add_u32 s98, s4, s14
	s_addc_u32 s99, s5, s15
	s_add_u32 s98, s98, 0x19c60000
	s_addc_u32 s99, s99, 0
	v_mov_b32_e32 v0, v185
	v_mov_b32_e32 v1, v185
	v_mov_b32_e32 v2, v185
	v_mov_b32_e32 v3, v185
	v_mov_b32_e32 v4, v185
	v_mov_b32_e32 v5, v185
	v_mov_b32_e32 v6, v185
	v_mov_b32_e32 v7, v185
	v_mov_b32_e32 v8, v185
	v_mov_b32_e32 v9, v185
	v_mov_b32_e32 v10, v185
	v_mov_b32_e32 v11, v185
	v_mov_b32_e32 v12, v185
	v_mov_b32_e32 v13, v185
	v_mov_b64_e32 v[30:31], v[14:15]
	v_mov_b64_e32 v[46:47], v[14:15]
	v_mov_b64_e32 v[62:63], v[14:15]
	s_mov_b32 s2, 4
	v_mov_b32_e32 v210, 0
	v_mov_b32_e32 v221, s24
	v_mov_b64_e32 v[28:29], v[12:13]
	v_mov_b64_e32 v[26:27], v[10:11]
	v_mov_b64_e32 v[24:25], v[8:9]
	v_mov_b64_e32 v[22:23], v[6:7]
	v_mov_b64_e32 v[20:21], v[4:5]
	v_mov_b64_e32 v[18:19], v[2:3]
	v_mov_b64_e32 v[16:17], v[0:1]
	v_mov_b64_e32 v[44:45], v[12:13]
	v_mov_b64_e32 v[42:43], v[10:11]
	v_mov_b64_e32 v[40:41], v[8:9]
	v_mov_b64_e32 v[38:39], v[6:7]
	v_mov_b64_e32 v[36:37], v[4:5]
	v_mov_b64_e32 v[34:35], v[2:3]
	v_mov_b64_e32 v[32:33], v[0:1]
	v_mov_b64_e32 v[60:61], v[12:13]
	v_mov_b64_e32 v[58:59], v[10:11]
	v_mov_b64_e32 v[56:57], v[8:9]
	v_mov_b64_e32 v[54:55], v[6:7]
	v_mov_b64_e32 v[52:53], v[4:5]
	v_mov_b64_e32 v[50:51], v[2:3]
	v_mov_b64_e32 v[48:49], v[0:1]
	v_mov_b32_e32 v65, v64
	v_mov_b32_e32 v66, v64
	v_mov_b32_e32 v67, v64
	v_mov_b32_e32 v68, v64
	v_mov_b32_e32 v69, v64
	v_mov_b32_e32 v70, v64
	v_mov_b32_e32 v71, v64
	v_mov_b32_e32 v72, v64
	v_mov_b32_e32 v73, v64
	v_mov_b32_e32 v74, v64
	v_mov_b32_e32 v75, v64
	v_mov_b32_e32 v76, v64
	v_mov_b32_e32 v77, v64
	v_mov_b32_e32 v78, v64
	v_mov_b32_e32 v79, v64
	s_waitcnt lgkmcnt(0)
	s_barrier
; DI void finishSM(f32x16& p0, f32x16& p1, float alpha, float& l_reg, bf16x8& pa0, bf16x8& pa1, bf16x8& pa2, bf16x8& pa3) {
; #pragma unroll
;     for (int r = 0; r < 16; ++r) p1[r] = __builtin_amdgcn_exp2f(p1[r]);
;     float ps = 0;
; #pragma unroll
;     for (int r = 0; r < 16; ++r) ps += p0[r];
; #pragma unroll
;     for (int r = 0; r < 16; ++r) ps += p1[r];
;     { auto rr = __builtin_amdgcn_permlane32_swap(__float_as_uint(ps), __float_as_uint(ps), false, false);
;       ps = __uint_as_float(rr[0]) + __uint_as_float(rr[1]); }
;     l_reg = l_reg * alpha + ps;
;     ...
;     PK4(p0, 0, pa0); PK4(p0, 8, pa1); PK4(p1, 0, pa2); PK4(p1, 8, pa3);
;     ...
; }
; DI void qkt(f32x16& p0, f32x16& p1, const char* Ks, const bf16x8* qr, const f32x16& negm, int r32, int hi) {
;     { const bf16x8 b0 = *reinterpret_cast<const bf16x8*>(Ks + KSWZ(r32, hi * 16));
;       const bf16x8 b1 = *reinterpret_cast<const bf16x8*>(Ks + KSWZ(32 + r32, hi * 16));
;       p0 = __builtin_amdgcn_mfma_f32_32x32x16_bf16(b0, qr[0], negm, 0, 0, 0);
;       p1 = __builtin_amdgcn_mfma_f32_32x32x16_bf16(b1, qr[0], negm, 0, 0, 0); }
; #pragma unroll
;     for (int d0 = 1; d0 < 4; ++d0) { const int cb = (d0 * 16 + hi * 8) * 2;
;         const bf16x8 b0 = *reinterpret_cast<const bf16x8*>(Ks + KSWZ(r32, cb));
;         const bf16x8 b1 = *reinterpret_cast<const bf16x8*>(Ks + KSWZ(32 + r32, cb));
;         p0 = __builtin_amdgcn_mfma_f32_32x32x16_bf16(b0, qr[d0], p0, 0, 0, 0);
;         p1 = __builtin_amdgcn_mfma_f32_32x32x16_bf16(b1, qr[d0], p1, 0, 0, 0); }
; }
; DI int v_st(int k, int c) { const int kk = (k & ~0xC) | ((k & 4) << 1) | ((k & 8) >> 1); return ((kk >> 3) * 4 + (c >> 5)) * 512 + ((kk & 7) * 32 + (c & 31)) * 2; }
; DI int v_rd_base(int lane) { return ((lane & 3) << 3) | (((lane >> 2) & 3) << 6) | (((lane >> 4) & 1) << 5) | (((lane >> 5) & 1) << 8); }
; template <int OFF> DI s16x4 tr_read(int vb) { s16x4 r; asm volatile("ds_read_b64_tr_b16 %0, %1 offset:%2" : "=&v"(r) : "v"(vb), "i"(OFF) : "memory"); return r; }
; template <int D0> DI void pv_one(f32x16& od, int vb, bf16x8 pa0, bf16x8 pa1, bf16x8 pa2, bf16x8 pa3) {
;     const s16x4 l0 = tr_read<v_rd_off(D0, 0, 0)>(vb), h0 = tr_read<v_rd_off(D0, 0, 1)>(vb), l1 = tr_read<v_rd_off(D0, 1, 0)>(vb), h1 = tr_read<v_rd_off(D0, 1, 1)>(vb);
.LBB0_1038:
	ds_read_b128 v[80:83], v217 offset:40960
	ds_read_b128 v[84:87], v217 offset:45056
	v_exp_f32_e32 v88, v96
	v_exp_f32_e32 v89, v97
	v_exp_f32_e32 v90, v98
	s_waitcnt lgkmcnt(1)
	v_mfma_f32_32x32x16_bf16 v[128:143], v[80:83], v[148:151], v[64:79]
	v_exp_f32_e32 v91, v99
	v_exp_f32_e32 v92, v100
	v_exp_f32_e32 v93, v101
	v_exp_f32_e32 v94, v102
	v_exp_f32_e32 v95, v103
	v_exp_f32_e32 v96, v104
	v_exp_f32_e32 v97, v105
	s_waitcnt lgkmcnt(0)
	v_mfma_f32_32x32x16_bf16 v[112:127], v[84:87], v[148:151], v[64:79]
	ds_read_b128 v[80:83], v218 offset:40960
	ds_read_b128 v[84:87], v218 offset:45056
	v_exp_f32_e32 v98, v106
	v_exp_f32_e32 v99, v107
	v_exp_f32_e32 v100, v108
	v_exp_f32_e32 v101, v109
	v_exp_f32_e32 v102, v110
	v_exp_f32_e32 v103, v111
	s_waitcnt lgkmcnt(1)
	v_mfma_f32_32x32x16_bf16 v[128:143], v[80:83], v[144:147], v[128:143]
	s_waitcnt lgkmcnt(0)
	v_mfma_f32_32x32x16_bf16 v[112:127], v[84:87], v[144:147], v[112:127]
	ds_read_b128 v[80:83], v219 offset:40960
	ds_read_b128 v[84:87], v219 offset:45056
	s_waitcnt lgkmcnt(1)
	v_mfma_f32_32x32x16_bf16 v[128:143], v[80:83], v[152:155], v[128:143]
	s_waitcnt lgkmcnt(0)
	v_mfma_f32_32x32x16_bf16 v[112:127], v[84:87], v[152:155], v[112:127]
	ds_read_b128 v[80:83], v216 offset:40960
	ds_read_b128 v[84:87], v216 offset:45056
	s_waitcnt lgkmcnt(1)
	v_mfma_f32_32x32x16_bf16 v[128:143], v[80:83], v[156:159], v[128:143]
	v_add_f32_e32 v80, v209, v207
	v_add_f32_e32 v80, v183, v80
	v_add_f32_e32 v80, v208, v80
	v_add_f32_e32 v80, v181, v80
	v_add_f32_e32 v80, v206, v80
	v_add_f32_e32 v80, v180, v80
	v_add_f32_e32 v80, v182, v80
	v_add_f32_e32 v80, v173, v80
	v_add_f32_e32 v80, v175, v80
	v_add_f32_e32 v80, v172, v80
	v_add_f32_e32 v80, v174, v80
	v_add_f32_e32 v80, v177, v80
	v_add_f32_e32 v80, v179, v80
	v_add_f32_e32 v80, v176, v80
	v_add_f32_e32 v80, v178, v80
	v_add_f32_e32 v80, v88, v80
	v_add_f32_e32 v80, v89, v80
	v_add_f32_e32 v80, v90, v80
	v_add_f32_e32 v80, v91, v80
	v_add_f32_e32 v80, v92, v80
	v_add_f32_e32 v80, v93, v80
	v_add_f32_e32 v80, v94, v80
	v_add_f32_e32 v80, v95, v80
	v_add_f32_e32 v80, v96, v80
	v_add_f32_e32 v80, v97, v80
	s_waitcnt lgkmcnt(0)
	v_mfma_f32_32x32x16_bf16 v[112:127], v[84:87], v[156:159], v[112:127]
	v_add_f32_e32 v80, v98, v80
	v_add_f32_e32 v80, v99, v80
	v_add_f32_e32 v80, v100, v80
	v_add_f32_e32 v80, v101, v80
	v_add_f32_e32 v80, v102, v80
	v_add_f32_e32 v222, v103, v80
	v_mov_b32_e32 v223, v222
	v_cvt_pk_bf16_f32 v80, v207, v209
	v_cvt_pk_bf16_f32 v81, v183, v208
	v_cvt_pk_bf16_f32 v82, v181, v206
	s_nop 1
	v_permlane32_swap_b32_e32 v222, v223
	v_cvt_pk_bf16_f32 v83, v180, v182
	v_permlane32_swap_b32_e32 v80, v82
	v_cvt_pk_bf16_f32 v84, v173, v175
	v_cvt_pk_bf16_f32 v85, v172, v174
	v_cvt_pk_bf16_f32 v86, v177, v179
	v_cvt_pk_bf16_f32 v87, v176, v178
	v_cvt_pk_bf16_f32 v88, v88, v89
	v_cvt_pk_bf16_f32 v89, v90, v91
	v_cvt_pk_bf16_f32 v90, v92, v93
	v_cvt_pk_bf16_f32 v91, v94, v95
	v_cvt_pk_bf16_f32 v92, v96, v97
	v_cvt_pk_bf16_f32 v93, v98, v99
	v_cvt_pk_bf16_f32 v94, v100, v101
	v_cvt_pk_bf16_f32 v95, v102, v103
	v_permlane32_swap_b32_e32 v81, v83
	v_permlane32_swap_b32_e32 v84, v86
	v_permlane32_swap_b32_e32 v85, v87
	v_permlane32_swap_b32_e32 v88, v90
	v_permlane32_swap_b32_e32 v89, v91
	v_permlane32_swap_b32_e32 v92, v94
	v_permlane32_swap_b32_e32 v93, v95
	global_load_dwordx4 v[172:175], v203, s[98:99]
	global_load_dwordx4 v[176:179], v204, s[98:99]
	global_load_dwordx4 v[180:183], v202, s[100:101]
	s_add_u32 s98, s98, 0x20000
	s_addc_u32 s99, s99, 0
	s_add_u32 s100, s100, 0x20000
	s_addc_u32 s101, s101, 0
	ds_read_b64_tr_b16 v[96:97], v220 offset:0
	ds_read_b64_tr_b16 v[98:99], v220 offset:0x800
	ds_read_b64_tr_b16 v[100:101], v220 offset:0x1000
	ds_read_b64_tr_b16 v[102:103], v220 offset:0x1800
	ds_read_b64_tr_b16 v[104:105], v220 offset:0x2000
	ds_read_b64_tr_b16 v[106:107], v220 offset:0x2800
	ds_read_b64_tr_b16 v[108:109], v220 offset:0x3000
	ds_read_b64_tr_b16 v[110:111], v220 offset:0x3800
	s_waitcnt lgkmcnt(0)
; #define SBAR() __builtin_amdgcn_sched_barrier(0)
; template <int OFF> DI s16x4 tr_read(int vb) { s16x4 r; asm volatile("ds_read_b64_tr_b16 %0, %1 offset:%2" : "=&v"(r) : "v"(vb), "i"(OFF) : "memory"); return r; }
; DI void partialSM(f32x16& p0, f32x16& p1, float& m_reg, f32x16& negm, float& alpha) {
;     constexpr float THR2 = THR * 1.4426950408889634f;
;     float pmax = p0[0];
; #pragma unroll
;     for (int r = 1; r < 16; ++r) pmax = fmaxf(pmax, p0[r]);
; #pragma unroll
;     for (int r = 0; r < 16; ++r) pmax = fmaxf(pmax, p1[r]);
;     { auto rr = __builtin_amdgcn_permlane32_swap(__float_as_uint(pmax), __float_as_uint(pmax), false, false);
;       pmax = fmaxf(__uint_as_float(rr[0]), __uint_as_float(rr[1])); }
;     const bool first = m_reg < -1e29f;
;     if (__builtin_expect(__all(!first && pmax <= THR2), 1)) { alpha = 1.f; }
; template <int D0> DI void pv_one(f32x16& od, int vb, bf16x8 pa0, bf16x8 pa1, bf16x8 pa2, bf16x8 pa3) {
;     const s16x4 l0 = tr_read<v_rd_off(D0, 0, 0)>(vb), h0 = tr_read<v_rd_off(D0, 0, 1)>(vb), l1 = tr_read<v_rd_off(D0, 1, 0)>(vb), h1 = tr_read<v_rd_off(D0, 1, 1)>(vb);
;     const s16x4 l2 = tr_read<v_rd_off(D0, 2, 0)>(vb), h2 = tr_read<v_rd_off(D0, 2, 1)>(vb), l3 = tr_read<v_rd_off(D0, 3, 0)>(vb), h3 = tr_read<v_rd_off(D0, 3, 1)>(vb);
;     asm volatile("s_waitcnt lgkmcnt(0)" ::: "memory"); SBAR();
;     ...
;     od = __builtin_amdgcn_mfma_f32_32x32x16_bf16(pa0, PKV(l0, h0), od, 0, 0, 0);
;     od = __builtin_amdgcn_mfma_f32_32x32x16_bf16(pa1, PKV(l1, h1), od, 0, 0, 0);
;     od = __builtin_amdgcn_mfma_f32_32x32x16_bf16(pa2, PKV(l2, h2), od, 0, 0, 0);
;     od = __builtin_amdgcn_mfma_f32_32x32x16_bf16(pa3, PKV(l3, h3), od, 0, 0, 0);
;     ...
; }
; DI void pv_d0(f32x16* o, int vb, bf16x8 pa0, bf16x8 pa1, bf16x8 pa2, bf16x8 pa3) {
;     pv_one<0>(o[0], vb, pa0, pa1, pa2, pa3); pv_one<1>(o[1], vb, pa0, pa1, pa2, pa3); pv_one<2>(o[2], vb, pa0, pa1, pa2, pa3); pv_one<3>(o[3], vb, pa0, pa1, pa2, pa3);
	s_nop 0
	v_mfma_f32_32x32x16_bf16 v[48:63], v[80:83], v[96:99], v[48:63]
	ds_read_b64_tr_b16 v[96:97], v220 offset:0x200
	ds_read_b64_tr_b16 v[98:99], v220 offset:0xa00
	v_mfma_f32_32x32x16_bf16 v[48:63], v[84:87], v[100:103], v[48:63]
	ds_read_b64_tr_b16 v[100:101], v220 offset:0x1200
	ds_read_b64_tr_b16 v[102:103], v220 offset:0x1a00
	v_mfma_f32_32x32x16_bf16 v[48:63], v[88:91], v[104:107], v[48:63]
	ds_read_b64_tr_b16 v[104:105], v220 offset:0x2200
	ds_read_b64_tr_b16 v[106:107], v220 offset:0x2a00
	v_mfma_f32_32x32x16_bf16 v[48:63], v[92:95], v[108:111], v[48:63]
	ds_read_b64_tr_b16 v[108:109], v220 offset:0x3200
	ds_read_b64_tr_b16 v[110:111], v220 offset:0x3a00
	s_waitcnt lgkmcnt(0)
	v_mfma_f32_32x32x16_bf16 v[32:47], v[80:83], v[96:99], v[32:47]
	ds_read_b64_tr_b16 v[96:97], v220 offset:0x400
	ds_read_b64_tr_b16 v[98:99], v220 offset:0xc00
	v_mfma_f32_32x32x16_bf16 v[32:47], v[84:87], v[100:103], v[32:47]
	ds_read_b64_tr_b16 v[100:101], v220 offset:0x1400
	ds_read_b64_tr_b16 v[102:103], v220 offset:0x1c00
	v_mfma_f32_32x32x16_bf16 v[32:47], v[88:91], v[104:107], v[32:47]
	ds_read_b64_tr_b16 v[104:105], v220 offset:0x2400
	ds_read_b64_tr_b16 v[106:107], v220 offset:0x2c00
	v_mfma_f32_32x32x16_bf16 v[32:47], v[92:95], v[108:111], v[32:47]
	ds_read_b64_tr_b16 v[108:109], v220 offset:0x3400
	ds_read_b64_tr_b16 v[110:111], v220 offset:0x3c00
	s_waitcnt lgkmcnt(0)
	v_mfma_f32_32x32x16_bf16 v[16:31], v[80:83], v[96:99], v[16:31]
	ds_read_b64_tr_b16 v[96:97], v220 offset:0x600
	ds_read_b64_tr_b16 v[98:99], v220 offset:0xe00
	v_mfma_f32_32x32x16_bf16 v[16:31], v[84:87], v[100:103], v[16:31]
	ds_read_b64_tr_b16 v[100:101], v220 offset:0x1600
	ds_read_b64_tr_b16 v[102:103], v220 offset:0x1e00
	v_mfma_f32_32x32x16_bf16 v[16:31], v[88:91], v[104:107], v[16:31]
	ds_read_b64_tr_b16 v[104:105], v220 offset:0x2600
	ds_read_b64_tr_b16 v[106:107], v220 offset:0x2e00
	v_mfma_f32_32x32x16_bf16 v[16:31], v[92:95], v[108:111], v[16:31]
	ds_read_b64_tr_b16 v[108:109], v220 offset:0x3600
	ds_read_b64_tr_b16 v[110:111], v220 offset:0x3e00
	s_waitcnt lgkmcnt(0)
	v_mfma_f32_32x32x16_bf16 v[0:15], v[80:83], v[96:99], v[0:15]
	v_max_f32_e32 v80, v128, v129
	v_max3_f32 v80, v80, v130, v131
	v_max3_f32 v80, v80, v132, v133
	v_max3_f32 v80, v80, v134, v135
	v_max3_f32 v80, v80, v136, v137
	v_mfma_f32_32x32x16_bf16 v[0:15], v[84:87], v[100:103], v[0:15]
	v_max3_f32 v80, v80, v138, v139
	v_max3_f32 v80, v80, v140, v141
	v_max3_f32 v80, v80, v142, v143
	v_max3_f32 v80, v80, v112, v113
	v_max3_f32 v80, v80, v114, v115
	v_max3_f32 v80, v80, v116, v117
	v_max3_f32 v80, v80, v118, v119
	v_mfma_f32_32x32x16_bf16 v[0:15], v[88:91], v[104:107], v[0:15]
	v_max3_f32 v80, v80, v120, v121
	v_max3_f32 v80, v80, v122, v123
	v_max3_f32 v80, v80, v124, v125
	v_max3_f32 v80, v80, v126, v127
	v_mov_b32_e32 v81, v80
	s_nop 1
	v_permlane32_swap_b32_e32 v80, v81
	v_mfma_f32_32x32x16_bf16 v[0:15], v[92:95], v[108:111], v[0:15]
	v_max_f32_e32 v80, v80, v81
	v_cmp_ngt_f32_e32 vcc, s83, v200
	v_cmp_ge_f32_e64 s[8:9], s63, v80
	s_and_b64 s[4:5], vcc, s[8:9]
	s_cmp_eq_u64 s[4:5], exec
	s_cbranch_scc0 .LBB0_1057
	v_mov_b32_e32 v224, 1.0

; #define SBAR() __builtin_amdgcn_sched_barrier(0)
; #define SLOADA(k0) do { vsA0 = *reinterpret_cast<const bf16x8*>(&Vh[(size_t)((k0) + sr) * LDQ + sc]); vsA1 = *reinterpret_cast<const bf16x8*>(&Vh[(size_t)((k0) + 32 + sr) * LDQ + sc]); \
;     ksA = *reinterpret_cast<const bf16x8*>(&Kh[(size_t)((k0) + kr) * LDQ + kc]); } while (0)
; DI void partialSM(f32x16& p0, f32x16& p1, float& m_reg, f32x16& negm, float& alpha) {
;     ...
;     for (int r = 0; r < 16; ++r) p0[r] = __builtin_amdgcn_exp2f(p0[r]);
; }
; DI void finishSM(f32x16& p0, f32x16& p1, float alpha, float& l_reg, bf16x8& pa0, bf16x8& pa1, bf16x8& pa2, bf16x8& pa3) {
; #pragma unroll
;     for (int r = 0; r < 16; ++r) p1[r] = __builtin_amdgcn_exp2f(p1[r]);
;     float ps = 0;
; #pragma unroll
;     for (int r = 0; r < 16; ++r) ps += p0[r];
; #pragma unroll
;     for (int r = 0; r < 16; ++r) ps += p1[r];
;     { auto rr = __builtin_amdgcn_permlane32_swap(__float_as_uint(ps), __float_as_uint(ps), false, false);
;       ps = __uint_as_float(rr[0]) + __uint_as_float(rr[1]); }
;     l_reg = l_reg * alpha + ps;
;     ...
;     PK4(p0, 0, pa0); PK4(p0, 8, pa1); PK4(p1, 0, pa2); PK4(p1, 8, pa3);
;     ...
; }
; DI void qkt(f32x16& p0, f32x16& p1, const char* Ks, const bf16x8* qr, const f32x16& negm, int r32, int hi) {
;     { const bf16x8 b0 = *reinterpret_cast<const bf16x8*>(Ks + KSWZ(r32, hi * 16));
;       const bf16x8 b1 = *reinterpret_cast<const bf16x8*>(Ks + KSWZ(32 + r32, hi * 16));
;       p0 = __builtin_amdgcn_mfma_f32_32x32x16_bf16(b0, qr[0], negm, 0, 0, 0);
;       p1 = __builtin_amdgcn_mfma_f32_32x32x16_bf16(b1, qr[0], negm, 0, 0, 0); }
; #pragma unroll
;     for (int d0 = 1; d0 < 4; ++d0) { const int cb = (d0 * 16 + hi * 8) * 2;
;         const bf16x8 b0 = *reinterpret_cast<const bf16x8*>(Ks + KSWZ(r32, cb));
;         const bf16x8 b1 = *reinterpret_cast<const bf16x8*>(Ks + KSWZ(32 + r32, cb));
;         p0 = __builtin_amdgcn_mfma_f32_32x32x16_bf16(b0, qr[d0], p0, 0, 0, 0);
;         p1 = __builtin_amdgcn_mfma_f32_32x32x16_bf16(b1, qr[d0], p1, 0, 0, 0); }
; }
; DI void attn_pass(const bf16_t* __restrict__ Qb, const bf16_t* __restrict__ Kh, const bf16_t* __restrict__ Vh, int seq, char* lds, f32x16 (&o)[4], float& l_out) {
;     ...
;         SBAR(); qkt(pA0, pA1, K_lds, qr, negm, r32, hi);
;         finishSM(pB0, pB1, alB, l_reg, pa0, pa1, pa2, pa3); SBAR();
;         if (j + 3 < NT) SLOADA((j + 3) * KVBLK); SBAR();
.LBB0_1044:
	v_exp_f32_e32 v246, v128
	v_exp_f32_e32 v248, v129
	v_exp_f32_e32 v244, v130
	v_exp_f32_e32 v247, v131
	v_exp_f32_e32 v236, v132
	v_exp_f32_e32 v245, v133
	v_exp_f32_e32 v235, v134
	v_exp_f32_e32 v237, v135
	v_exp_f32_e32 v232, v136
	v_exp_f32_e32 v234, v137
	v_exp_f32_e32 v230, v138
	v_exp_f32_e32 v233, v139
	v_exp_f32_e32 v228, v140
	v_exp_f32_e32 v231, v141
	v_exp_f32_e32 v227, v142
	v_exp_f32_e32 v229, v143
	s_waitcnt lgkmcnt(0)
	s_barrier
	ds_read_b128 v[96:99], v217 offset:32768
	ds_read_b128 v[250:253], v217 offset:36864
	v_exp_f32_e32 v249, v120
	v_exp_f32_e32 v254, v121
	v_exp_f32_e32 v186, v122
	s_waitcnt lgkmcnt(1)
	v_mfma_f32_32x32x16_bf16 v[128:143], v[96:99], v[148:151], v[64:79]
	v_exp_f32_e32 v187, v123
	v_exp_f32_e32 v188, v124
	v_exp_f32_e32 v189, v125
	v_exp_f32_e32 v194, v126
	v_exp_f32_e32 v127, v127
	s_waitcnt lgkmcnt(0)
	v_mfma_f32_32x32x16_bf16 v[96:111], v[250:253], v[148:151], v[64:79]
	ds_read_b128 v[250:253], v218 offset:32768
	ds_read_b128 v[238:241], v218 offset:36864
	s_waitcnt lgkmcnt(1)
	v_mfma_f32_32x32x16_bf16 v[128:143], v[250:253], v[144:147], v[128:143]
	s_waitcnt lgkmcnt(0)
	v_mfma_f32_32x32x16_bf16 v[96:111], v[238:241], v[144:147], v[96:111]
	ds_read_b128 v[238:241], v219 offset:32768
	ds_read_b128 v[250:253], v219 offset:36864
	s_waitcnt lgkmcnt(1)
	v_mfma_f32_32x32x16_bf16 v[128:143], v[238:241], v[152:155], v[128:143]
	s_waitcnt lgkmcnt(0)
	v_mfma_f32_32x32x16_bf16 v[96:111], v[250:253], v[152:155], v[96:111]
	ds_read_b128 v[238:241], v216 offset:32768
	ds_read_b128 v[250:253], v216 offset:36864
	s_waitcnt lgkmcnt(1)
	v_mfma_f32_32x32x16_bf16 v[128:143], v[238:241], v[156:159], v[128:143]
	v_exp_f32_e32 v238, v112
	v_add_f32_e32 v112, v248, v246
	v_add_f32_e32 v112, v244, v112
	v_add_f32_e32 v112, v247, v112
	v_add_f32_e32 v112, v236, v112
	v_add_f32_e32 v112, v245, v112
	v_add_f32_e32 v112, v235, v112
	v_add_f32_e32 v112, v237, v112
	v_add_f32_e32 v112, v232, v112
	v_add_f32_e32 v112, v234, v112
	v_add_f32_e32 v112, v230, v112
	v_add_f32_e32 v112, v233, v112
	v_add_f32_e32 v112, v228, v112
	v_exp_f32_e32 v239, v113
	v_add_f32_e32 v112, v231, v112
	v_exp_f32_e32 v240, v114
	v_add_f32_e32 v112, v227, v112
	v_exp_f32_e32 v241, v115
	v_add_f32_e32 v112, v229, v112
	s_waitcnt lgkmcnt(0)
	v_mfma_f32_32x32x16_bf16 v[96:111], v[250:253], v[156:159], v[96:111]
	v_exp_f32_e32 v250, v116
	v_add_f32_e32 v112, v238, v112
	v_exp_f32_e32 v251, v117
	v_add_f32_e32 v112, v239, v112
	v_exp_f32_e32 v252, v118
	v_add_f32_e32 v112, v240, v112
	v_exp_f32_e32 v253, v119
	v_add_f32_e32 v112, v241, v112
	v_add_f32_e32 v112, v250, v112
	v_add_f32_e32 v112, v251, v112
	v_add_f32_e32 v112, v252, v112
	v_add_f32_e32 v112, v253, v112
	v_add_f32_e32 v112, v249, v112
	v_add_f32_e32 v112, v254, v112
	v_add_f32_e32 v112, v186, v112
	v_add_f32_e32 v112, v187, v112
	v_add_f32_e32 v112, v188, v112
	v_add_f32_e32 v112, v189, v112
	v_add_f32_e32 v112, v194, v112
	v_add_f32_e32 v225, v127, v112
	v_mov_b32_e32 v226, v225
	v_cvt_pk_bf16_f32 v112, v246, v248
	v_cvt_pk_bf16_f32 v113, v244, v247
	v_cvt_pk_bf16_f32 v114, v236, v245
	v_cvt_pk_bf16_f32 v115, v235, v237
	v_cvt_pk_bf16_f32 v116, v232, v234
	v_cvt_pk_bf16_f32 v117, v230, v233
	v_cvt_pk_bf16_f32 v118, v228, v231
	v_cvt_pk_bf16_f32 v119, v227, v229
	v_cvt_pk_bf16_f32 v120, v238, v239
	v_cvt_pk_bf16_f32 v121, v240, v241
	v_cvt_pk_bf16_f32 v122, v250, v251
	v_cvt_pk_bf16_f32 v123, v252, v253
	v_cvt_pk_bf16_f32 v124, v249, v254
	v_cvt_pk_bf16_f32 v125, v186, v187
	v_cvt_pk_bf16_f32 v126, v188, v189
	v_cvt_pk_bf16_f32 v127, v194, v127
	s_nop 1
	v_permlane32_swap_b32_e32 v225, v226
	v_permlane32_swap_b32_e32 v112, v114
	v_permlane32_swap_b32_e32 v113, v115
	v_permlane32_swap_b32_e32 v116, v118
	v_permlane32_swap_b32_e32 v117, v119
	v_permlane32_swap_b32_e32 v120, v122
	v_permlane32_swap_b32_e32 v121, v123
	v_permlane32_swap_b32_e32 v124, v126
	v_permlane32_swap_b32_e32 v125, v127
	s_cmp_ge_u32 s2, s22
	s_cselect_b64 s[4:5], -1, 0
	s_and_b64 vcc, exec, s[4:5]
	s_cbranch_vccnz .LBB0_1046
	global_load_dwordx4 v[160:163], v203, s[98:99]
	global_load_dwordx4 v[164:167], v204, s[98:99]
	global_load_dwordx4 v[168:171], v202, s[100:101]
; #define SBAR() __builtin_amdgcn_sched_barrier(0)
; template <int OFF> DI s16x4 tr_read(int vb) { s16x4 r; asm volatile("ds_read_b64_tr_b16 %0, %1 offset:%2" : "=&v"(r) : "v"(vb), "i"(OFF) : "memory"); return r; }
; DI void partialSM(f32x16& p0, f32x16& p1, float& m_reg, f32x16& negm, float& alpha) {
;     constexpr float THR2 = THR * 1.4426950408889634f;
;     float pmax = p0[0];
; #pragma unroll
;     for (int r = 1; r < 16; ++r) pmax = fmaxf(pmax, p0[r]);
; #pragma unroll
;     for (int r = 0; r < 16; ++r) pmax = fmaxf(pmax, p1[r]);
;     { auto rr = __builtin_amdgcn_permlane32_swap(__float_as_uint(pmax), __float_as_uint(pmax), false, false);
;       pmax = fmaxf(__uint_as_float(rr[0]), __uint_as_float(rr[1])); }
;     const bool first = m_reg < -1e29f;
;     if (__builtin_expect(__all(!first && pmax <= THR2), 1)) { alpha = 1.f; }
; template <int D0> DI void pv_one(f32x16& od, int vb, bf16x8 pa0, bf16x8 pa1, bf16x8 pa2, bf16x8 pa3) {
;     const s16x4 l0 = tr_read<v_rd_off(D0, 0, 0)>(vb), h0 = tr_read<v_rd_off(D0, 0, 1)>(vb), l1 = tr_read<v_rd_off(D0, 1, 0)>(vb), h1 = tr_read<v_rd_off(D0, 1, 1)>(vb);
;     const s16x4 l2 = tr_read<v_rd_off(D0, 2, 0)>(vb), h2 = tr_read<v_rd_off(D0, 2, 1)>(vb), l3 = tr_read<v_rd_off(D0, 3, 0)>(vb), h3 = tr_read<v_rd_off(D0, 3, 1)>(vb);
;     asm volatile("s_waitcnt lgkmcnt(0)" ::: "memory"); SBAR();
;     ...
;     od = __builtin_amdgcn_mfma_f32_32x32x16_bf16(pa0, PKV(l0, h0), od, 0, 0, 0);
;     od = __builtin_amdgcn_mfma_f32_32x32x16_bf16(pa1, PKV(l1, h1), od, 0, 0, 0);
;     od = __builtin_amdgcn_mfma_f32_32x32x16_bf16(pa2, PKV(l2, h2), od, 0, 0, 0);
;     od = __builtin_amdgcn_mfma_f32_32x32x16_bf16(pa3, PKV(l3, h3), od, 0, 0, 0);
;     ...
; }
; DI void pv_d0(f32x16* o, int vb, bf16x8 pa0, bf16x8 pa1, bf16x8 pa2, bf16x8 pa3) {
;     pv_one<0>(o[0], vb, pa0, pa1, pa2, pa3); pv_one<1>(o[1], vb, pa0, pa1, pa2, pa3); pv_one<2>(o[2], vb, pa0, pa1, pa2, pa3); pv_one<3>(o[3], vb, pa0, pa1, pa2, pa3);
.LBB0_1046:
	s_add_u32 s98, s98, 0x20000
	s_addc_u32 s99, s99, 0
	s_add_u32 s100, s100, 0x20000
	s_addc_u32 s101, s101, 0
	ds_read_b64_tr_b16 v[206:207], v201 offset:0
	ds_read_b64_tr_b16 v[208:209], v201 offset:0x800
	ds_read_b64_tr_b16 v[228:229], v201 offset:0x1000
	ds_read_b64_tr_b16 v[230:231], v201 offset:0x1800
	ds_read_b64_tr_b16 v[232:233], v201 offset:0x2000
	ds_read_b64_tr_b16 v[234:235], v201 offset:0x2800
	ds_read_b64_tr_b16 v[236:237], v201 offset:0x3000
	ds_read_b64_tr_b16 v[238:239], v201 offset:0x3800
	s_waitcnt lgkmcnt(0)
	s_nop 0
	v_mfma_f32_32x32x16_bf16 v[48:63], v[112:115], v[206:209], v[48:63]
	ds_read_b64_tr_b16 v[206:207], v201 offset:0x200
	ds_read_b64_tr_b16 v[208:209], v201 offset:0xa00
	v_mfma_f32_32x32x16_bf16 v[48:63], v[116:119], v[228:231], v[48:63]
	ds_read_b64_tr_b16 v[228:229], v201 offset:0x1200
	ds_read_b64_tr_b16 v[230:231], v201 offset:0x1a00
	v_mfma_f32_32x32x16_bf16 v[48:63], v[120:123], v[232:235], v[48:63]
	ds_read_b64_tr_b16 v[232:233], v201 offset:0x2200
	ds_read_b64_tr_b16 v[234:235], v201 offset:0x2a00
	v_mfma_f32_32x32x16_bf16 v[48:63], v[124:127], v[236:239], v[48:63]
	ds_read_b64_tr_b16 v[236:237], v201 offset:0x3200
	ds_read_b64_tr_b16 v[238:239], v201 offset:0x3a00
	s_waitcnt lgkmcnt(0)
	v_mfma_f32_32x32x16_bf16 v[32:47], v[112:115], v[206:209], v[32:47]
	ds_read_b64_tr_b16 v[206:207], v201 offset:0x400
	ds_read_b64_tr_b16 v[208:209], v201 offset:0xc00
	v_mfma_f32_32x32x16_bf16 v[32:47], v[116:119], v[228:231], v[32:47]
	ds_read_b64_tr_b16 v[228:229], v201 offset:0x1400
	ds_read_b64_tr_b16 v[230:231], v201 offset:0x1c00
	v_mfma_f32_32x32x16_bf16 v[32:47], v[120:123], v[232:235], v[32:47]
	ds_read_b64_tr_b16 v[232:233], v201 offset:0x2400
	ds_read_b64_tr_b16 v[234:235], v201 offset:0x2c00
	v_mfma_f32_32x32x16_bf16 v[32:47], v[124:127], v[236:239], v[32:47]
	ds_read_b64_tr_b16 v[236:237], v201 offset:0x3400
	ds_read_b64_tr_b16 v[238:239], v201 offset:0x3c00
	s_waitcnt lgkmcnt(0)
	v_mfma_f32_32x32x16_bf16 v[16:31], v[112:115], v[206:209], v[16:31]
	ds_read_b64_tr_b16 v[206:207], v201 offset:0x600
	ds_read_b64_tr_b16 v[208:209], v201 offset:0xe00
	v_mfma_f32_32x32x16_bf16 v[16:31], v[116:119], v[228:231], v[16:31]
	ds_read_b64_tr_b16 v[228:229], v201 offset:0x1600
	ds_read_b64_tr_b16 v[230:231], v201 offset:0x1e00
	v_mfma_f32_32x32x16_bf16 v[16:31], v[120:123], v[232:235], v[16:31]
	ds_read_b64_tr_b16 v[232:233], v201 offset:0x2600
	ds_read_b64_tr_b16 v[234:235], v201 offset:0x2e00
	v_mfma_f32_32x32x16_bf16 v[16:31], v[124:127], v[236:239], v[16:31]
	ds_read_b64_tr_b16 v[236:237], v201 offset:0x3600
	ds_read_b64_tr_b16 v[238:239], v201 offset:0x3e00
	s_waitcnt lgkmcnt(0)
	v_mfma_f32_32x32x16_bf16 v[0:15], v[112:115], v[206:209], v[0:15]
	v_max_f32_e32 v112, v128, v129
	v_max3_f32 v112, v112, v130, v131
	v_max3_f32 v112, v112, v132, v133
	v_max3_f32 v112, v112, v134, v135
	v_max3_f32 v112, v112, v136, v137
	v_mfma_f32_32x32x16_bf16 v[0:15], v[116:119], v[228:231], v[0:15]
	v_max3_f32 v112, v112, v138, v139
	v_max3_f32 v112, v112, v140, v141
	v_max3_f32 v112, v112, v142, v143
	v_max3_f32 v112, v112, v96, v97
	v_max3_f32 v112, v112, v98, v99
	v_max3_f32 v112, v112, v100, v101
	v_max3_f32 v112, v112, v102, v103
	v_mfma_f32_32x32x16_bf16 v[0:15], v[120:123], v[232:235], v[0:15]
	v_max3_f32 v112, v112, v104, v105
	v_max3_f32 v112, v112, v106, v107
	v_max3_f32 v112, v112, v108, v109
	v_max3_f32 v112, v112, v110, v111
	v_mov_b32_e32 v113, v112
	s_nop 1
	v_permlane32_swap_b32_e32 v112, v113
	v_mfma_f32_32x32x16_bf16 v[0:15], v[124:127], v[236:239], v[0:15]
	v_max_f32_e32 v113, v112, v113
	v_cmp_ngt_f32_e32 vcc, s83, v200
	v_cmp_ge_f32_e64 s[8:9], s63, v113
	s_and_b64 s[8:9], vcc, s[8:9]
	s_cmp_eq_u64 s[8:9], exec
	v_mov_b32_e32 v112, 1.0
	s_cbranch_scc0 .LBB0_1058

; #define SBAR() __builtin_amdgcn_sched_barrier(0)
; #define SLOADA(k0) do { vsA0 = *reinterpret_cast<const bf16x8*>(&Vh[(size_t)((k0) + sr) * LDQ + sc]); vsA1 = *reinterpret_cast<const bf16x8*>(&Vh[(size_t)((k0) + 32 + sr) * LDQ + sc]); \
;     ksA = *reinterpret_cast<const bf16x8*>(&Kh[(size_t)((k0) + kr) * LDQ + kc]); } while (0)
; #define SLOADB(k0) do { vsB0 = *reinterpret_cast<const bf16x8*>(&Vh[(size_t)((k0) + sr) * LDQ + sc]); vsB1 = *reinterpret_cast<const bf16x8*>(&Vh[(size_t)((k0) + 32 + sr) * LDQ + sc]); \
;     ksB = *reinterpret_cast<const bf16x8*>(&Kh[(size_t)((k0) + kr) * LDQ + kc]); } while (0)
; #define SWRITEA(b) do { *(bf16x8*)(V_lds + (b) * SHM_V + vst0) = vsA0; *(bf16x8*)(V_lds + (b) * SHM_V + vst1) = vsA1; *(bf16x8*)(K_lds + (b) * SHM_K + kst) = ksA; } while (0)
; #define SWRITEB(b) do { *(bf16x8*)(V_lds + (b) * SHM_V + vst0) = vsB0; *(bf16x8*)(V_lds + (b) * SHM_V + vst1) = vsB1; *(bf16x8*)(K_lds + (b) * SHM_K + kst) = ksB; } while (0)
; #define SWAIT() asm volatile("s_waitcnt vmcnt(3)" ::: "memory")
; #define RESC(a) do { if (__any((a) < 1.f)) { if (hi == 0) al_l[r32] = (a); asm volatile("s_waitcnt lgkmcnt(0)" ::: "memory"); \
;     _Pragma("unroll") for (int d = 0; d < 4; ++d) _Pragma("unroll") for (int r = 0; r < 16; ++r) o[d][r] *= al_l[crow(r, hi)]; } } while (0)
; DI void attn_pass(const bf16_t* __restrict__ Qb, const bf16_t* __restrict__ Kh, const bf16_t* __restrict__ Vh, int seq, char* lds, f32x16 (&o)[4], float& l_out) {
;     ...
;     for (int j = 1; j + 1 < NT; j += 2) {
;         SBAR(); qkt(pB0, pB1, K_lds + SHM_K, qr, negm, r32, hi);
;         finishSM(pA0, pA1, alA, l_reg, pa0, pa1, pa2, pa3); SBAR();
;         SLOADB((j + 2) * KVBLK); SBAR();
;         pv_d0(o, vb0, pa0, pa1, pa2, pa3); partialSM(pB0, pB1, m_reg, negm, alB);
;         __syncthreads(); SWAIT(); SWRITEA(0);
;         RESC(alB); __syncthreads();
;         SBAR(); qkt(pA0, pA1, K_lds, qr, negm, r32, hi);
;         finishSM(pB0, pB1, alB, l_reg, pa0, pa1, pa2, pa3); SBAR();
;         if (j + 3 < NT) SLOADA((j + 3) * KVBLK); SBAR();
;         pv_d0(o, vb0 + SHM_V, pa0, pa1, pa2, pa3); partialSM(pA0, pA1, m_reg, negm, alA);
;         __syncthreads(); if (j + 3 < NT) SWAIT(); else asm volatile("s_waitcnt vmcnt(0)" ::: "memory"); SWRITEB(1);
;         RESC(alA); __syncthreads();
;     }
.LBB0_1055:
	v_exp_f32_e32 v207, v128
	v_exp_f32_e32 v209, v129
	v_exp_f32_e32 v183, v130
	v_exp_f32_e32 v208, v131
	v_exp_f32_e32 v181, v132
	v_exp_f32_e32 v206, v133
	v_exp_f32_e32 v180, v134
	v_exp_f32_e32 v182, v135
	v_exp_f32_e32 v173, v136
	v_exp_f32_e32 v175, v137
	v_exp_f32_e32 v172, v138
	v_exp_f32_e32 v174, v139
	v_exp_f32_e32 v177, v140
	v_exp_f32_e32 v179, v141
	v_exp_f32_e32 v176, v142
	v_exp_f32_e32 v178, v143
	v_add_f32_e32 v113, v222, v223
	v_fmac_f32_e32 v113, v221, v210
	v_add_f32_e32 v210, v225, v226
	v_fmac_f32_e32 v210, v113, v224
	s_add_i32 s2, s2, 2
	s_and_b64 vcc, exec, s[4:5]
	s_waitcnt lgkmcnt(0)
	s_barrier
	s_cbranch_vccnz .LBB0_1059
	v_mov_b32_e32 v221, v112
	s_branch .LBB0_1038
